# v034 + accumulator zeroing with 64 v_mov_b64 instead of 128 v_mov_b32 per tile in the six GEMM instances
# speedup vs baseline: 1.0068x; 1.0032x over previous
.LBB0_133:
	s_ashr_i32 s19, s18, 31
	s_lshl_b64 s[28:29], s[18:19], 19
	v_cmp_lt_i64_e32 vcc, s[62:63], v[182:183]
	s_add_u32 s62, s27, s28
	s_addc_u32 s63, s37, s29
	s_and_b64 s[28:29], vcc, exec
	s_cselect_b32 s5, s63, s67
	s_cselect_b32 s7, s62, s66
	s_ashr_i32 s17, s16, 31
	s_lshl_b64 s[28:29], s[16:17], 19
	s_add_u32 s64, s46, s28
	s_addc_u32 s65, s47, s29
	s_and_b64 s[28:29], vcc, exec
	s_cselect_b32 s17, s65, s69
	s_cselect_b32 s19, s64, s68
	s_add_u32 s66, s66, 0x40080
	s_addc_u32 s67, s67, 0
	s_add_u32 s85, s68, 0x100
	v_mov_b64_e32 v[0:1], 0
	v_mov_b64_e32 v[2:3], 0
	v_mov_b64_e32 v[4:5], 0
	v_mov_b64_e32 v[6:7], 0
	v_mov_b64_e32 v[8:9], 0
	v_mov_b64_e32 v[10:11], 0
	v_mov_b64_e32 v[12:13], 0
	v_mov_b64_e32 v[14:15], 0
	v_mov_b64_e32 v[16:17], 0
	v_mov_b64_e32 v[18:19], 0
	v_mov_b64_e32 v[20:21], 0
	v_mov_b64_e32 v[22:23], 0
	v_mov_b64_e32 v[24:25], 0
	v_mov_b64_e32 v[26:27], 0
	v_mov_b64_e32 v[28:29], 0
	v_mov_b64_e32 v[30:31], 0
	v_mov_b64_e32 v[32:33], 0
	v_mov_b64_e32 v[34:35], 0
	v_mov_b64_e32 v[36:37], 0
	v_mov_b64_e32 v[38:39], 0
	v_mov_b64_e32 v[40:41], 0
	v_mov_b64_e32 v[42:43], 0
	v_mov_b64_e32 v[44:45], 0
	v_mov_b64_e32 v[46:47], 0
	v_mov_b64_e32 v[48:49], 0
	v_mov_b64_e32 v[50:51], 0
	v_mov_b64_e32 v[52:53], 0
	v_mov_b64_e32 v[54:55], 0
	v_mov_b64_e32 v[56:57], 0
	v_mov_b64_e32 v[58:59], 0
	v_mov_b64_e32 v[60:61], 0
	v_mov_b64_e32 v[62:63], 0
	v_mov_b64_e32 v[64:65], 0
	v_mov_b64_e32 v[66:67], 0
	v_mov_b64_e32 v[68:69], 0
	v_mov_b64_e32 v[70:71], 0
	v_mov_b64_e32 v[72:73], 0
	v_mov_b64_e32 v[74:75], 0
	v_mov_b64_e32 v[76:77], 0
	v_mov_b64_e32 v[78:79], 0
	v_mov_b64_e32 v[80:81], 0
	v_mov_b64_e32 v[82:83], 0
	v_mov_b64_e32 v[84:85], 0
	v_mov_b64_e32 v[86:87], 0
	v_mov_b64_e32 v[88:89], 0
	v_mov_b64_e32 v[90:91], 0
	v_mov_b64_e32 v[92:93], 0
	v_mov_b64_e32 v[94:95], 0
	v_mov_b64_e32 v[96:97], 0
	v_mov_b64_e32 v[98:99], 0
	v_mov_b64_e32 v[100:101], 0
	v_mov_b64_e32 v[102:103], 0
	v_mov_b64_e32 v[104:105], 0
	v_mov_b64_e32 v[106:107], 0
	v_mov_b64_e32 v[108:109], 0
	v_mov_b64_e32 v[110:111], 0
	v_mov_b64_e32 v[112:113], 0
	v_mov_b64_e32 v[114:115], 0
	v_mov_b64_e32 v[116:117], 0
	v_mov_b64_e32 v[118:119], 0
	v_mov_b64_e32 v[120:121], 0
	v_mov_b64_e32 v[122:123], 0
	v_mov_b64_e32 v[124:125], 0
	v_mov_b64_e32 v[126:127], 0
	s_addc_u32 s91, s69, 0
	s_mov_b32 vcc_lo, -2
	s_waitcnt vmcnt(0)

.LBB0_412:
	s_add_i32 s13, s67, -2
	s_add_u32 s85, s62, 0x100
	v_mov_b64_e32 v[0:1], 0
	v_mov_b64_e32 v[2:3], 0
	v_mov_b64_e32 v[4:5], 0
	v_mov_b64_e32 v[6:7], 0
	v_mov_b64_e32 v[8:9], 0
	v_mov_b64_e32 v[10:11], 0
	v_mov_b64_e32 v[12:13], 0
	v_mov_b64_e32 v[14:15], 0
	v_mov_b64_e32 v[16:17], 0
	v_mov_b64_e32 v[18:19], 0
	v_mov_b64_e32 v[20:21], 0
	v_mov_b64_e32 v[22:23], 0
	v_mov_b64_e32 v[24:25], 0
	v_mov_b64_e32 v[26:27], 0
	v_mov_b64_e32 v[28:29], 0
	v_mov_b64_e32 v[30:31], 0
	v_mov_b64_e32 v[32:33], 0
	v_mov_b64_e32 v[34:35], 0
	v_mov_b64_e32 v[36:37], 0
	v_mov_b64_e32 v[38:39], 0
	v_mov_b64_e32 v[40:41], 0
	v_mov_b64_e32 v[42:43], 0
	v_mov_b64_e32 v[44:45], 0
	v_mov_b64_e32 v[46:47], 0
	v_mov_b64_e32 v[48:49], 0
	v_mov_b64_e32 v[50:51], 0
	v_mov_b64_e32 v[52:53], 0
	v_mov_b64_e32 v[54:55], 0
	v_mov_b64_e32 v[56:57], 0
	v_mov_b64_e32 v[58:59], 0
	v_mov_b64_e32 v[60:61], 0
	v_mov_b64_e32 v[62:63], 0
	v_mov_b64_e32 v[64:65], 0
	v_mov_b64_e32 v[66:67], 0
	v_mov_b64_e32 v[68:69], 0
	v_mov_b64_e32 v[70:71], 0
	v_mov_b64_e32 v[72:73], 0
	v_mov_b64_e32 v[74:75], 0
	v_mov_b64_e32 v[76:77], 0
	v_mov_b64_e32 v[78:79], 0
	v_mov_b64_e32 v[80:81], 0
	v_mov_b64_e32 v[82:83], 0
	v_mov_b64_e32 v[84:85], 0
	v_mov_b64_e32 v[86:87], 0
	v_mov_b64_e32 v[88:89], 0
	v_mov_b64_e32 v[90:91], 0
	v_mov_b64_e32 v[92:93], 0
	v_mov_b64_e32 v[94:95], 0
	v_mov_b64_e32 v[96:97], 0
	v_mov_b64_e32 v[98:99], 0
	v_mov_b64_e32 v[100:101], 0
	v_mov_b64_e32 v[102:103], 0
	v_mov_b64_e32 v[104:105], 0
	v_mov_b64_e32 v[106:107], 0
	v_mov_b64_e32 v[108:109], 0
	v_mov_b64_e32 v[110:111], 0
	v_mov_b64_e32 v[112:113], 0
	v_mov_b64_e32 v[114:115], 0
	v_mov_b64_e32 v[116:117], 0
	v_mov_b64_e32 v[118:119], 0
	v_mov_b64_e32 v[120:121], 0
	v_mov_b64_e32 v[122:123], 0
	v_mov_b64_e32 v[124:125], 0
	v_mov_b64_e32 v[126:127], 0
	s_addc_u32 s91, s63, 0
	s_mov_b32 s62, 0

.LBB0_504:
	v_mov_b64_e32 v[0:1], 0x3c6
	s_ashr_i32 s65, s64, 31
	v_cmp_lt_i64_e32 vcc, s[8:9], v[0:1]
	s_lshl_b64 s[8:9], s[64:65], 20
	s_add_u32 s66, s27, s8
	s_addc_u32 s67, s74, s9
	s_and_b64 s[8:9], vcc, exec
	s_cselect_b32 s10, s67, s5
	s_cselect_b32 s11, s66, s4
	s_ashr_i32 s63, s62, 31
	s_lshl_b64 s[8:9], s[62:63], 20
	s_add_u32 s68, s75, s8
	s_addc_u32 s69, s76, s9
	s_and_b64 s[8:9], vcc, exec
	s_cselect_b32 s63, s69, s7
	s_cselect_b32 s65, s68, s6
	s_add_u32 s4, s4, 0x80080
	s_addc_u32 s5, s5, 0
	s_add_u32 s70, s6, 0x100
	v_mov_b64_e32 v[0:1], 0
	v_mov_b64_e32 v[2:3], 0
	v_mov_b64_e32 v[4:5], 0
	v_mov_b64_e32 v[6:7], 0
	v_mov_b64_e32 v[8:9], 0
	v_mov_b64_e32 v[10:11], 0
	v_mov_b64_e32 v[12:13], 0
	v_mov_b64_e32 v[14:15], 0
	v_mov_b64_e32 v[16:17], 0
	v_mov_b64_e32 v[18:19], 0
	v_mov_b64_e32 v[20:21], 0
	v_mov_b64_e32 v[22:23], 0
	v_mov_b64_e32 v[24:25], 0
	v_mov_b64_e32 v[26:27], 0
	v_mov_b64_e32 v[28:29], 0
	v_mov_b64_e32 v[30:31], 0
	v_mov_b64_e32 v[32:33], 0
	v_mov_b64_e32 v[34:35], 0
	v_mov_b64_e32 v[36:37], 0
	v_mov_b64_e32 v[38:39], 0
	v_mov_b64_e32 v[40:41], 0
	v_mov_b64_e32 v[42:43], 0
	v_mov_b64_e32 v[44:45], 0
	v_mov_b64_e32 v[46:47], 0
	v_mov_b64_e32 v[48:49], 0
	v_mov_b64_e32 v[50:51], 0
	v_mov_b64_e32 v[52:53], 0
	v_mov_b64_e32 v[54:55], 0
	v_mov_b64_e32 v[56:57], 0
	v_mov_b64_e32 v[58:59], 0
	v_mov_b64_e32 v[60:61], 0
	v_mov_b64_e32 v[62:63], 0
	v_mov_b64_e32 v[64:65], 0
	v_mov_b64_e32 v[66:67], 0
	v_mov_b64_e32 v[68:69], 0
	v_mov_b64_e32 v[70:71], 0
	v_mov_b64_e32 v[72:73], 0
	v_mov_b64_e32 v[74:75], 0
	v_mov_b64_e32 v[76:77], 0
	v_mov_b64_e32 v[78:79], 0
	v_mov_b64_e32 v[80:81], 0
	v_mov_b64_e32 v[82:83], 0
	v_mov_b64_e32 v[84:85], 0
	v_mov_b64_e32 v[86:87], 0
	v_mov_b64_e32 v[88:89], 0
	v_mov_b64_e32 v[90:91], 0
	v_mov_b64_e32 v[92:93], 0
	v_mov_b64_e32 v[94:95], 0
	v_mov_b64_e32 v[96:97], 0
	v_mov_b64_e32 v[98:99], 0
	v_mov_b64_e32 v[100:101], 0
	v_mov_b64_e32 v[102:103], 0
	v_mov_b64_e32 v[104:105], 0
	v_mov_b64_e32 v[106:107], 0
	v_mov_b64_e32 v[108:109], 0
	v_mov_b64_e32 v[110:111], 0
	v_mov_b64_e32 v[112:113], 0
	v_mov_b64_e32 v[114:115], 0
	v_mov_b64_e32 v[116:117], 0
	v_mov_b64_e32 v[118:119], 0
	v_mov_b64_e32 v[120:121], 0
	v_mov_b64_e32 v[122:123], 0
	v_mov_b64_e32 v[124:125], 0
	v_mov_b64_e32 v[126:127], 0
	s_addc_u32 s71, s7, 0
	s_mov_b32 s72, -2

.LBB0_1113:
	s_add_i32 s85, s76, -2
	s_add_u32 s64, s64, 0x80
	s_addc_u32 s65, s65, 0
	s_add_u32 s91, s66, 0x100
	v_mov_b64_e32 v[0:1], 0
	v_mov_b64_e32 v[2:3], 0
	v_mov_b64_e32 v[4:5], 0
	v_mov_b64_e32 v[6:7], 0
	v_mov_b64_e32 v[8:9], 0
	v_mov_b64_e32 v[10:11], 0
	v_mov_b64_e32 v[12:13], 0
	v_mov_b64_e32 v[14:15], 0
	v_mov_b64_e32 v[16:17], 0
	v_mov_b64_e32 v[18:19], 0
	v_mov_b64_e32 v[20:21], 0
	v_mov_b64_e32 v[22:23], 0
	v_mov_b64_e32 v[24:25], 0
	v_mov_b64_e32 v[26:27], 0
	v_mov_b64_e32 v[28:29], 0
	v_mov_b64_e32 v[30:31], 0
	v_mov_b64_e32 v[32:33], 0
	v_mov_b64_e32 v[34:35], 0
	v_mov_b64_e32 v[36:37], 0
	v_mov_b64_e32 v[38:39], 0
	v_mov_b64_e32 v[40:41], 0
	v_mov_b64_e32 v[42:43], 0
	v_mov_b64_e32 v[44:45], 0
	v_mov_b64_e32 v[46:47], 0
	v_mov_b64_e32 v[48:49], 0
	v_mov_b64_e32 v[50:51], 0
	v_mov_b64_e32 v[52:53], 0
	v_mov_b64_e32 v[54:55], 0
	v_mov_b64_e32 v[56:57], 0
	v_mov_b64_e32 v[58:59], 0
	v_mov_b64_e32 v[60:61], 0
	v_mov_b64_e32 v[62:63], 0
	v_mov_b64_e32 v[64:65], 0
	v_mov_b64_e32 v[66:67], 0
	v_mov_b64_e32 v[68:69], 0
	v_mov_b64_e32 v[70:71], 0
	v_mov_b64_e32 v[72:73], 0
	v_mov_b64_e32 v[74:75], 0
	v_mov_b64_e32 v[76:77], 0
	v_mov_b64_e32 v[78:79], 0
	v_mov_b64_e32 v[80:81], 0
	v_mov_b64_e32 v[82:83], 0
	v_mov_b64_e32 v[84:85], 0
	v_mov_b64_e32 v[86:87], 0
	v_mov_b64_e32 v[88:89], 0
	v_mov_b64_e32 v[90:91], 0
	v_mov_b64_e32 v[92:93], 0
	v_mov_b64_e32 v[94:95], 0
	v_mov_b64_e32 v[96:97], 0
	v_mov_b64_e32 v[98:99], 0
	v_mov_b64_e32 v[100:101], 0
	v_mov_b64_e32 v[102:103], 0
	v_mov_b64_e32 v[104:105], 0
	v_mov_b64_e32 v[106:107], 0
	v_mov_b64_e32 v[108:109], 0
	v_mov_b64_e32 v[110:111], 0
	v_mov_b64_e32 v[112:113], 0
	v_mov_b64_e32 v[114:115], 0
	v_mov_b64_e32 v[116:117], 0
	v_mov_b64_e32 v[118:119], 0
	v_mov_b64_e32 v[120:121], 0
	v_mov_b64_e32 v[122:123], 0
	v_mov_b64_e32 v[124:125], 0
	v_mov_b64_e32 v[126:127], 0
	s_addc_u32 vcc_lo, s67, 0
	s_mov_b32 s66, 0

.LBB0_1281:
	s_add_i32 s5, s79, -2
	s_add_u32 s58, s58, 0x80
	s_addc_u32 s59, s59, 0
	s_add_u32 s21, s60, 0x100
	v_mov_b64_e32 v[0:1], 0
	v_mov_b64_e32 v[2:3], 0
	v_mov_b64_e32 v[4:5], 0
	v_mov_b64_e32 v[6:7], 0
	v_mov_b64_e32 v[8:9], 0
	v_mov_b64_e32 v[10:11], 0
	v_mov_b64_e32 v[12:13], 0
	v_mov_b64_e32 v[14:15], 0
	v_mov_b64_e32 v[16:17], 0
	v_mov_b64_e32 v[18:19], 0
	v_mov_b64_e32 v[20:21], 0
	v_mov_b64_e32 v[22:23], 0
	v_mov_b64_e32 v[24:25], 0
	v_mov_b64_e32 v[26:27], 0
	v_mov_b64_e32 v[28:29], 0
	v_mov_b64_e32 v[30:31], 0
	v_mov_b64_e32 v[32:33], 0
	v_mov_b64_e32 v[34:35], 0
	v_mov_b64_e32 v[36:37], 0
	v_mov_b64_e32 v[38:39], 0
	v_mov_b64_e32 v[40:41], 0
	v_mov_b64_e32 v[42:43], 0
	v_mov_b64_e32 v[44:45], 0
	v_mov_b64_e32 v[46:47], 0
	v_mov_b64_e32 v[48:49], 0
	v_mov_b64_e32 v[50:51], 0
	v_mov_b64_e32 v[52:53], 0
	v_mov_b64_e32 v[54:55], 0
	v_mov_b64_e32 v[56:57], 0
	v_mov_b64_e32 v[58:59], 0
	v_mov_b64_e32 v[60:61], 0
	v_mov_b64_e32 v[62:63], 0
	v_mov_b64_e32 v[64:65], 0
	v_mov_b64_e32 v[66:67], 0
	v_mov_b64_e32 v[68:69], 0
	v_mov_b64_e32 v[70:71], 0
	v_mov_b64_e32 v[72:73], 0
	v_mov_b64_e32 v[74:75], 0
	v_mov_b64_e32 v[76:77], 0
	v_mov_b64_e32 v[78:79], 0
	v_mov_b64_e32 v[80:81], 0
	v_mov_b64_e32 v[82:83], 0
	v_mov_b64_e32 v[84:85], 0
	v_mov_b64_e32 v[86:87], 0
	v_mov_b64_e32 v[88:89], 0
	v_mov_b64_e32 v[90:91], 0
	v_mov_b64_e32 v[92:93], 0
	v_mov_b64_e32 v[94:95], 0
	v_mov_b64_e32 v[96:97], 0
	v_mov_b64_e32 v[98:99], 0
	v_mov_b64_e32 v[100:101], 0
	v_mov_b64_e32 v[102:103], 0
	v_mov_b64_e32 v[104:105], 0
	v_mov_b64_e32 v[106:107], 0
	v_mov_b64_e32 v[108:109], 0
	v_mov_b64_e32 v[110:111], 0
	v_mov_b64_e32 v[112:113], 0
	v_mov_b64_e32 v[114:115], 0
	v_mov_b64_e32 v[116:117], 0
	v_mov_b64_e32 v[118:119], 0
	v_mov_b64_e32 v[120:121], 0
	v_mov_b64_e32 v[122:123], 0
	v_mov_b64_e32 v[124:125], 0
	v_mov_b64_e32 v[126:127], 0
	s_addc_u32 s80, s61, 0
	s_mov_b32 s60, 0
	s_waitcnt lgkmcnt(0)

.LBB0_1435:
	s_ashr_i32 s17, s16, 31
	v_cmp_lt_i64_e32 vcc, s[18:19], v[186:187]
	s_lshl_b64 s[18:19], s[16:17], 19
	s_add_u32 s18, s47, s18
	s_addc_u32 s19, s54, s19
	s_and_b64 s[20:21], vcc, exec
	s_cselect_b32 s17, s19, s7
	s_cselect_b32 s66, s18, s6
	s_ashr_i32 s13, s12, 31
	s_lshl_b64 s[20:21], s[12:13], 19
	s_add_u32 s20, s37, s20
	s_addc_u32 s21, s46, s21
	s_and_b64 s[52:53], vcc, exec
	s_cselect_b32 s13, s21, s51
	s_cselect_b32 s67, s20, s50
	s_add_u32 s6, s6, 0x40080
	s_addc_u32 s7, s7, 0
	s_add_u32 s68, s50, 0x100
	v_mov_b64_e32 v[0:1], 0
	v_mov_b64_e32 v[2:3], 0
	v_mov_b64_e32 v[4:5], 0
	v_mov_b64_e32 v[6:7], 0
	v_mov_b64_e32 v[8:9], 0
	v_mov_b64_e32 v[10:11], 0
	v_mov_b64_e32 v[12:13], 0
	v_mov_b64_e32 v[14:15], 0
	v_mov_b64_e32 v[16:17], 0
	v_mov_b64_e32 v[18:19], 0
	v_mov_b64_e32 v[20:21], 0
	v_mov_b64_e32 v[22:23], 0
	v_mov_b64_e32 v[24:25], 0
	v_mov_b64_e32 v[26:27], 0
	v_mov_b64_e32 v[28:29], 0
	v_mov_b64_e32 v[30:31], 0
	v_mov_b64_e32 v[32:33], 0
	v_mov_b64_e32 v[34:35], 0
	v_mov_b64_e32 v[36:37], 0
	v_mov_b64_e32 v[38:39], 0
	v_mov_b64_e32 v[40:41], 0
	v_mov_b64_e32 v[42:43], 0
	v_mov_b64_e32 v[44:45], 0
	v_mov_b64_e32 v[46:47], 0
	v_mov_b64_e32 v[48:49], 0
	v_mov_b64_e32 v[50:51], 0
	v_mov_b64_e32 v[52:53], 0
	v_mov_b64_e32 v[54:55], 0
	v_mov_b64_e32 v[56:57], 0
	v_mov_b64_e32 v[58:59], 0
	v_mov_b64_e32 v[60:61], 0
	v_mov_b64_e32 v[62:63], 0
	v_mov_b64_e32 v[64:65], 0
	v_mov_b64_e32 v[66:67], 0
	v_mov_b64_e32 v[68:69], 0
	v_mov_b64_e32 v[70:71], 0
	v_mov_b64_e32 v[72:73], 0
	v_mov_b64_e32 v[74:75], 0
	v_mov_b64_e32 v[76:77], 0
	v_mov_b64_e32 v[78:79], 0
	v_mov_b64_e32 v[80:81], 0
	v_mov_b64_e32 v[82:83], 0
	v_mov_b64_e32 v[84:85], 0
	v_mov_b64_e32 v[86:87], 0
	v_mov_b64_e32 v[88:89], 0
	v_mov_b64_e32 v[90:91], 0
	v_mov_b64_e32 v[92:93], 0
	v_mov_b64_e32 v[94:95], 0
	v_mov_b64_e32 v[96:97], 0
	v_mov_b64_e32 v[98:99], 0
	v_mov_b64_e32 v[100:101], 0
	v_mov_b64_e32 v[102:103], 0
	v_mov_b64_e32 v[104:105], 0
	v_mov_b64_e32 v[106:107], 0
	v_mov_b64_e32 v[108:109], 0
	v_mov_b64_e32 v[110:111], 0
	v_mov_b64_e32 v[112:113], 0
	v_mov_b64_e32 v[114:115], 0
	v_mov_b64_e32 v[116:117], 0
	v_mov_b64_e32 v[118:119], 0
	v_mov_b64_e32 v[120:121], 0
	v_mov_b64_e32 v[122:123], 0
	v_mov_b64_e32 v[124:125], 0
	v_mov_b64_e32 v[126:127], 0
	s_addc_u32 s69, s51, 0
	s_mov_b32 s70, -2
